# scan chunk loop: key-norm parameter loads issued before the next-chunk prefetch block; counted vmcnt(10) so the wait no longer forces the streaming prefetch to complete
# speedup vs baseline: 1.0422x; 1.0013x over previous
; __device__ __forceinline__ void scan_item(const Params& p, int stream, int h, unsigned char* smem) {
;     ...
;           if (first && shift0) {
; #pragma unroll
;             for (int j = 0; j < 8; ++j) pf[j] = shift0[1536 + lseg + hf * 8 + j];
;           }
.LBB0_1593:
	s_or_b64 exec, exec, s[34:35]


; DI float bflo(u32 v) { return __uint_as_float(v << 16); }
; DI float bfhi(u32 v) { return __uint_as_float(v & 0xffff0000u); }
; __device__ __forceinline__ void scan_item(const Params& p, int stream, int h, unsigned char* smem) {
;     ...
;           float cf[8], pf[8], lv[8];
; #pragma unroll
;           for (int j = 0; j < 4; ++j) {
;             cf[2 * j] = bflo(cc[j]); cf[2 * j + 1] = bfhi(cc[j]);
;             pf[2 * j] = bflo(pq[j]); pf[2 * j + 1] = bfhi(pq[j]);
;           }
;           if (first && shift0) {
; #pragma unroll
;             for (int j = 0; j < 8; ++j) pf[j] = shift0[1536 + lseg + hf * 8 + j];
;           }
;           const float4 m0 = *(const float4*)(mu + 1536 + lseg + hf * 8), m1 = *(const float4*)(mu + 1536 + lseg + hf * 8 + 4);
;           const float mul[8] = {m0.x, m0.y, m0.z, m0.w, m1.x, m1.y, m1.z, m1.w};
;           const float act_s = lseg < 64 ? 2.f : 1.f;
; #pragma unroll
;           for (int j = 0; j < 8; ++j) {
;             const float sft = cf[j] + mul[j] * (pf[j] - cf[j]);
;     ...
;       if (tb + 32 < T) SCAN_LOAD(t0 + 32);
	v_lshlrev_b32_e32 v0, 16, v52
	v_and_b32_e32 v1, 0xffff0000, v52
	v_lshlrev_b32_e32 v3, 16, v53
	v_and_b32_e32 v84, 0xffff0000, v53
	v_lshlrev_b32_e32 v85, 16, v54
	v_and_b32_e32 v86, 0xffff0000, v54
	v_lshlrev_b32_e32 v87, 16, v55
	v_and_b32_e32 v88, 0xffff0000, v55
	s_waitcnt vmcnt(0)
	v_sub_f32_e32 v68, v68, v0
	v_sub_f32_e32 v69, v69, v1
	v_sub_f32_e32 v70, v70, v3
	v_sub_f32_e32 v71, v71, v84
	v_sub_f32_e32 v72, v72, v85
	v_sub_f32_e32 v73, v73, v86
	v_sub_f32_e32 v74, v74, v87
	v_sub_f32_e32 v75, v75, v88
	s_add_i32 s74, s66, 32
	s_cmp_ge_u32 s74, s40
	s_cselect_b64 s[60:61], -1, 0
	s_and_b64 vcc, exec, s[60:61]

; __device__ __forceinline__ void scan_item(const Params& p, int stream, int h, unsigned char* smem) {
;     ...
;           const float4 m0 = *(const float4*)(mu + 1536 + lseg + hf * 8), m1 = *(const float4*)(mu + 1536 + lseg + hf * 8 + 4);
;           const float mul[8] = {m0.x, m0.y, m0.z, m0.w, m1.x, m1.y, m1.z, m1.w};
;           const float act_s = lseg < 64 ? 2.f : 1.f;
; #pragma unroll
;           for (int j = 0; j < 8; ++j) {
;             const float sft = cf[j] + mul[j] * (pf[j] - cf[j]);
	v_fmac_f32_e32 v0, v68, v248
	v_fmac_f32_e32 v1, v69, v249
	v_fmac_f32_e32 v3, v70, v250
	v_fmac_f32_e32 v84, v71, v251

; DI float frcp(float x) { return __builtin_amdgcn_rcpf(x); }
; __device__ __forceinline__ void scan_item(const Params& p, int stream, int h, unsigned char* smem) {
;     ...
;           const float4 m0 = *(const float4*)(mu + 1536 + lseg + hf * 8), m1 = *(const float4*)(mu + 1536 + lseg + hf * 8 + 4);
;           const float mul[8] = {m0.x, m0.y, m0.z, m0.w, m1.x, m1.y, m1.z, m1.w};
;           const float act_s = lseg < 64 ? 2.f : 1.f;
; #pragma unroll
;           for (int j = 0; j < 8; ++j) {
;             const float sft = cf[j] + mul[j] * (pf[j] - cf[j]);
;             const float sg = frcp(1.f + __expf(-act_s * sft));
;             lv[j] = lseg < 64 ? 2.f * sg - 1.f : (lseg >= 128 ? sg : sft);
;           }
;           u32x4 w0 = {pack2(lv[0], lv[1]), pack2(lv[2], lv[3]), pack2(lv[4], lv[5]), pack2(lv[6], lv[7])};
;           *(u32x4*)(base + (st << 10) + swz(et, c4 + hf)) = w0;
;         }
;       }
;       if (tb + 32 < T) SCAN_LOAD(t0 + 32);
	v_fmac_f32_e32 v85, v72, v252
	v_fmac_f32_e32 v86, v73, v253
	v_fmac_f32_e32 v87, v74, v254
	v_fmac_f32_e32 v88, v75, v255
	v_mul_f32_e32 v68, v198, v0
	v_mul_f32_e32 v69, v198, v1
	v_mul_f32_e32 v70, v198, v3
	v_mul_f32_e32 v71, v198, v84
	v_mul_f32_e32 v72, v198, v85
	v_mul_f32_e32 v73, v198, v86
	v_mul_f32_e32 v74, v198, v87
	v_mul_f32_e32 v75, v198, v88
	v_mul_f32_e32 v68, 0x3fb8aa3b, v68
	v_mul_f32_e32 v69, 0x3fb8aa3b, v69
	v_mul_f32_e32 v70, 0x3fb8aa3b, v70
	v_mul_f32_e32 v71, 0x3fb8aa3b, v71
	v_mul_f32_e32 v72, 0x3fb8aa3b, v72
	v_mul_f32_e32 v73, 0x3fb8aa3b, v73
	v_mul_f32_e32 v74, 0x3fb8aa3b, v74
	v_mul_f32_e32 v75, 0x3fb8aa3b, v75
	v_exp_f32_e32 v68, v68
	v_exp_f32_e32 v69, v69
	v_exp_f32_e32 v70, v70
	v_exp_f32_e32 v71, v71
	v_exp_f32_e32 v72, v72
	v_exp_f32_e32 v73, v73
	v_exp_f32_e32 v74, v74
	v_exp_f32_e32 v75, v75
	v_add_f32_e32 v68, 1.0, v68
	v_add_f32_e32 v69, 1.0, v69
	v_add_f32_e32 v70, 1.0, v70
	v_add_f32_e32 v71, 1.0, v71
	v_add_f32_e32 v72, 1.0, v72
	v_add_f32_e32 v73, 1.0, v73
	v_add_f32_e32 v74, 1.0, v74
	v_add_f32_e32 v75, 1.0, v75
	v_rcp_f32_e32 v68, v68
	v_rcp_f32_e32 v69, v69
	v_rcp_f32_e32 v70, v70
	v_rcp_f32_e32 v71, v71
	v_rcp_f32_e32 v72, v72
	v_rcp_f32_e32 v73, v73
	v_rcp_f32_e32 v74, v74
	v_rcp_f32_e32 v75, v75
	v_fma_f32 v76, v68, 2.0, -1.0
	v_cndmask_b32_e64 v0, v0, v68, s[4:5]
	v_fma_f32 v68, v69, 2.0, -1.0
	v_cndmask_b32_e64 v1, v1, v69, s[4:5]
	v_fma_f32 v69, v70, 2.0, -1.0
	v_cndmask_b32_e64 v3, v3, v70, s[4:5]
	v_fma_f32 v70, v71, 2.0, -1.0
	v_cndmask_b32_e64 v71, v84, v71, s[4:5]
	v_fma_f32 v77, v72, 2.0, -1.0
	v_cndmask_b32_e64 v72, v85, v72, s[4:5]
	v_fma_f32 v78, v73, 2.0, -1.0
	v_cndmask_b32_e64 v73, v86, v73, s[4:5]
	v_fma_f32 v79, v74, 2.0, -1.0
	v_cndmask_b32_e64 v74, v87, v74, s[4:5]
	v_fma_f32 v80, v75, 2.0, -1.0
	v_cndmask_b32_e64 v75, v88, v75, s[4:5]
	v_cndmask_b32_e64 v0, v0, v76, s[2:3]
	v_cndmask_b32_e64 v1, v1, v68, s[2:3]
	v_cndmask_b32_e64 v3, v3, v69, s[2:3]
	v_cndmask_b32_e64 v69, v71, v70, s[2:3]
	v_cndmask_b32_e64 v70, v72, v77, s[2:3]
	v_cndmask_b32_e64 v71, v73, v78, s[2:3]
	v_cndmask_b32_e64 v72, v74, v79, s[2:3]
	v_cndmask_b32_e64 v73, v75, v80, s[2:3]
	v_cvt_pk_bf16_f32 v68, v0, v1
	v_cvt_pk_bf16_f32 v69, v3, v69
	v_cvt_pk_bf16_f32 v70, v70, v71
	v_cvt_pk_bf16_f32 v71, v72, v73
	ds_write_b128 v220, v[68:71]
	global_load_dwordx4 v[240:243], v[154:155], off
	global_load_dwordx4 v[244:247], v[156:157], off
	global_load_dwordx4 v[248:251], v[158:159], off
	s_cbranch_vccnz .LBB0_1595
	v_add_u32_e32 v0, 32, v170
	v_ashrrev_i32_e32 v1, 31, v0
	v_lshl_add_u64 v[0:1], v[124:125], 0, v[0:1]
	v_cmp_gt_i64_e32 vcc, s[48:49], v[0:1]
	v_mov_b64_e32 v[52:53], s[24:25]
	v_mov_b32_e32 v167, v2
	v_cndmask_b32_e32 v56, v184, v0, vcc
	v_mad_u64_u32 v[52:53], s[0:1], v56, s94, v[52:53]
	v_cndmask_b32_e32 v3, 0, v1, vcc
	v_mov_b32_e32 v54, v53
	v_mad_u64_u32 v[54:55], s[0:1], v3, s94, v[54:55]
	v_mov_b32_e32 v53, v54
	v_mov_b64_e32 v[54:55], s[50:51]
	v_mad_u64_u32 v[54:55], s[0:1], v56, s95, v[54:55]
	v_mov_b32_e32 v56, v55
	v_mad_u64_u32 v[56:57], s[0:1], v3, s95, v[56:57]
	v_cmp_lt_i64_e32 vcc, 0, v[0:1]
	v_mov_b32_e32 v169, v2
	s_nop 0
	v_cndmask_b32_e32 v1, 0, v56, vcc
	v_cndmask_b32_e32 v0, 0, v54, vcc
	v_lshl_add_u64 v[0:1], v[0:1], 1, s[24:25]
	v_lshl_add_u64 v[54:55], v[52:53], 0, v[166:167]
	v_lshl_add_u64 v[56:57], v[0:1], 0, v[166:167]
	global_load_dwordx2 v[100:101], v[54:55], off
	global_load_dwordx2 v[102:103], v[56:57], off
	global_load_dwordx2 v[104:105], v[54:55], off offset:1024
	global_load_dwordx2 v[106:107], v[54:55], off offset:2048
	global_load_dwordx2 v[108:109], v[56:57], off offset:1024
	global_load_dwordx2 v[110:111], v[56:57], off offset:2048
	v_lshl_add_u64 v[56:57], v[52:53], 0, v[168:169]
	v_lshl_add_u64 v[0:1], v[0:1], 0, v[168:169]
	global_load_dwordx4 v[52:55], v[56:57], off offset:3088
	s_nop 0
	global_load_dwordx4 v[56:59], v[56:57], off offset:3072
	s_nop 0
	global_load_dwordx4 v[60:63], v[0:1], off offset:3088
	global_load_dwordx4 v[64:67], v[0:1], off offset:3072
.LBB0_1595:


; DI float sigmoidf_(float x) { return frcp(1.f + __expf(-x)); }
; DI f32x4 mfma16(bf16x8 a, bf16x8 b, f32x4 c) { return __builtin_amdgcn_mfma_f32_16x16x32_bf16(a, b, c, 0, 0, 0); }
; __device__ __forceinline__ void scan_item(const Params& p, int stream, int h, unsigned char* smem) {
;     ...
;     {
;       f32x4 dw = {0.f, 0.f, 0.f, 0.f}, da = dw, dg = dw;
; #pragma unroll
;       for (int ks = 0; ks < 2; ++ks) {
;         bf16x8 aw = *(const bf16x8*)(sTW + (ks << 10) + swz(r, q));
;         bf16x8 aa = *(const bf16x8*)(sAL + (ks << 10) + swz(r, q));
;         dw = mfma16(aw, bw[ks], dw);
;         da = mfma16(aa, ba[ks], da);
;       }
; #pragma unroll
;       for (int ks = 0; ks < 4; ++ks) {
;         bf16x8 ag = *(const bf16x8*)(sSG + (ks << 10) + swz(r, q));
;         dg = mfma16(ag, bg[ks], dg);
;       }
;       const int ch = wave * 16 + r;
; #pragma unroll
;       for (int jj = 0; jj < 4; ++jj) {
;         const int tk = q * 4 + jj;
;         float z = -(w0c + dw[jj]);
;         float sp = z > 20.f ? z : __logf(1.f + __expf(z));
;         float logw = -sp - 0.5f;
;         sW[tk * 64 + ch] = __expf(-__expf(logw));
;         sKKA[tk * 64 + ch] = sigmoidf_(a0c + da[jj]);
;         sG[tk * 64 + ch] = dg[jj];
;       }
;     }
	s_waitcnt lgkmcnt(0)
	s_barrier
	ds_read_b128 v[68:71], v222 offset:37120
	ds_read_b128 v[72:75], v222 offset:38144
	ds_read_b128 v[76:79], v221 offset:33024
	ds_read_b128 v[80:83], v221 offset:34048
	s_waitcnt lgkmcnt(1)
	v_mfma_f32_16x16x32_bf16 v[76:79], v[76:79], v[4:7], 0
	s_waitcnt lgkmcnt(0)
	v_mfma_f32_16x16x32_bf16 v[76:79], v[80:83], v[8:11], v[76:79]
	ds_read_b128 v[80:83], v221 offset:36096
	v_mfma_f32_16x16x32_bf16 v[68:71], v[68:71], v[20:23], 0
	v_mfma_f32_16x16x32_bf16 v[68:71], v[72:75], v[24:27], v[68:71]
	s_nop 4
	v_add_f32_e32 v0, v93, v76
	v_mul_f32_e32 v1, 0xbfb8aa3b, v0
	v_exp_f32_e32 v1, v1
	ds_read_b128 v[72:75], v221 offset:35072
	s_waitcnt lgkmcnt(0)
	v_mfma_f32_16x16x32_bf16 v[72:75], v[72:75], v[12:15], 0
	v_add_f32_e32 v1, 1.0, v1
	v_cmp_gt_f32_e32 vcc, s63, v1
	ds_read_b128 v[84:87], v222 offset:39168
	ds_read_b128 v[88:91], v222 offset:40192
	v_cndmask_b32_e64 v3, 0, 32, vcc
	v_ldexp_f32 v1, v1, v3
	v_log_f32_e32 v1, v1
	v_add_f32_e32 v3, v93, v77
	v_cndmask_b32_e32 v76, 0, v193, vcc
	v_mfma_f32_16x16x32_bf16 v[72:75], v[80:83], v[16:19], v[72:75]
	v_mul_f32_e32 v77, 0x3f317217, v1
	v_fma_f32 v77, v1, s64, -v77
	v_fmac_f32_e32 v77, 0x3377d1cf, v1
	v_fmac_f32_e32 v77, 0x3f317217, v1
	v_cmp_lt_f32_e64 vcc, |v1|, s65
	s_nop 2
	v_add_f32_e32 v72, v97, v72
	v_mul_f32_e32 v72, 0xbfb8aa3b, v72
	v_cndmask_b32_e32 v1, v1, v77, vcc
	v_sub_f32_e32 v1, v1, v76
	v_cmp_gt_f32_e32 vcc, s62, v0
	v_exp_f32_e32 v72, v72
	v_add_f32_e32 v73, v97, v73
	v_cndmask_b32_e64 v0, v1, -v0, vcc
	v_mul_f32_e32 v1, 0xbfb8aa3b, v3
	v_exp_f32_e32 v1, v1
	v_sub_f32_e32 v0, -0.5, v0
	v_mul_f32_e32 v0, 0x3fb8aa3b, v0
	v_exp_f32_e32 v0, v0
	v_add_f32_e32 v1, 1.0, v1
	v_cmp_gt_f32_e32 vcc, s63, v1
	v_mul_f32_e32 v73, 0xbfb8aa3b, v73
	v_mul_f32_e32 v0, 0xbfb8aa3b, v0
	v_cndmask_b32_e64 v76, 0, 32, vcc
	v_ldexp_f32 v1, v1, v76
	v_log_f32_e32 v1, v1
	v_exp_f32_e32 v0, v0
	v_exp_f32_e32 v73, v73
	v_add_f32_e32 v74, v97, v74
	v_mul_f32_e32 v76, 0x3f317217, v1
	v_fma_f32 v76, v1, s64, -v76
	v_fmac_f32_e32 v76, 0x3377d1cf, v1
	v_fmac_f32_e32 v76, 0x3f317217, v1
	v_cmp_lt_f32_e64 s[0:1], |v1|, s65
	s_waitcnt lgkmcnt(1)
	v_mfma_f32_16x16x32_bf16 v[68:71], v[84:87], v[28:31], v[68:71]
	v_mul_f32_e32 v74, 0xbfb8aa3b, v74
	v_cndmask_b32_e64 v1, v1, v76, s[0:1]
	v_cndmask_b32_e32 v76, 0, v193, vcc
	v_sub_f32_e32 v1, v1, v76
	v_cmp_gt_f32_e32 vcc, s62, v3
	v_exp_f32_e32 v74, v74
	s_waitcnt lgkmcnt(0)
	v_mfma_f32_16x16x32_bf16 v[68:71], v[88:91], v[32:35], v[68:71]
	v_cndmask_b32_e64 v1, v1, -v3, vcc
	v_add_f32_e32 v3, 1.0, v72
	v_add_f32_e32 v72, v93, v78
	v_mul_f32_e32 v76, 0xbfb8aa3b, v72
	v_exp_f32_e32 v76, v76
	v_sub_f32_e32 v1, -0.5, v1
	v_mul_f32_e32 v1, 0x3fb8aa3b, v1
	v_exp_f32_e32 v1, v1
	v_add_f32_e32 v76, 1.0, v76
	v_cmp_gt_f32_e32 vcc, s63, v76
	v_rcp_f32_e32 v3, v3
	v_mul_f32_e32 v1, 0xbfb8aa3b, v1
	v_cndmask_b32_e64 v77, 0, 32, vcc
	v_ldexp_f32 v76, v76, v77
	v_exp_f32_e32 v1, v1
	v_log_f32_e32 v76, v76
	v_add_f32_e32 v74, 1.0, v74
	v_rcp_f32_e32 v74, v74
	ds_write2st64_b32 v205, v0, v1 offset1:1
	v_mul_f32_e32 v1, 0x3f317217, v76
	v_fma_f32 v1, v76, s64, -v1
	v_fmac_f32_e32 v1, 0x3377d1cf, v76
	v_fmac_f32_e32 v1, 0x3f317217, v76
	v_cmp_lt_f32_e64 s[0:1], |v76|, s65
	v_add_f32_e32 v0, 1.0, v73
	v_cndmask_b32_e32 v73, 0, v193, vcc
	v_cndmask_b32_e64 v1, v76, v1, s[0:1]
	v_sub_f32_e32 v1, v1, v73
	v_cmp_gt_f32_e32 vcc, s62, v72
	v_rcp_f32_e32 v0, v0
	s_nop 0
	v_cndmask_b32_e64 v1, v1, -v72, vcc
	v_add_f32_e32 v72, v93, v79
	v_mul_f32_e32 v73, 0xbfb8aa3b, v72
	v_exp_f32_e32 v73, v73
	v_sub_f32_e32 v1, -0.5, v1
	v_mul_f32_e32 v1, 0x3fb8aa3b, v1
	v_exp_f32_e32 v1, v1
	v_add_f32_e32 v73, 1.0, v73
	v_cmp_gt_f32_e32 vcc, s63, v73
	v_mul_f32_e32 v1, 0xbfb8aa3b, v1
	s_nop 0
	v_cndmask_b32_e64 v76, 0, 32, vcc
	v_ldexp_f32 v73, v73, v76
	v_log_f32_e32 v73, v73
	v_exp_f32_e32 v1, v1
	v_mul_f32_e32 v76, 0x3f317217, v73
	v_fma_f32 v76, v73, s64, -v76
	v_fmac_f32_e32 v76, 0x3377d1cf, v73
	v_fmac_f32_e32 v76, 0x3f317217, v73
	v_cmp_lt_f32_e64 s[0:1], |v73|, s65
	s_nop 1
	v_cndmask_b32_e64 v73, v73, v76, s[0:1]
	v_cndmask_b32_e32 v76, 0, v193, vcc
	v_sub_f32_e32 v73, v73, v76
	v_cmp_gt_f32_e32 vcc, s62, v72
	s_nop 1
	v_cndmask_b32_e64 v72, v73, -v72, vcc
	v_sub_f32_e32 v72, -0.5, v72
	v_mul_f32_e32 v72, 0x3fb8aa3b, v72
	v_add_f32_e32 v73, v97, v75
	v_exp_f32_e32 v72, v72
	v_mul_f32_e32 v73, 0xbfb8aa3b, v73
	v_exp_f32_e32 v73, v73
	v_mul_f32_e32 v72, 0xbfb8aa3b, v72
	v_exp_f32_e32 v72, v72
	v_add_f32_e32 v73, 1.0, v73
	v_rcp_f32_e32 v73, v73
	ds_write2st64_b32 v205, v3, v0 offset0:48 offset1:49
	ds_write2st64_b32 v205, v68, v69 offset0:96 offset1:97
	ds_write2st64_b32 v205, v1, v72 offset0:2 offset1:3
	ds_write2st64_b32 v205, v74, v73 offset0:50 offset1:51
	ds_write2st64_b32 v205, v70, v71 offset0:98 offset1:99
	s_waitcnt lgkmcnt(0)
	s_barrier


; __device__ __forceinline__ void scan_item(const Params& p, int stream, int h, unsigned char* smem) {
;     ...
;       float4 k4 = *(const float4*)(sKp + et * 64 + ec);
;       float4 a4 = *(const float4*)(sKKA + et * 64 + ec);
;       float4 r4 = *(const float4*)(sR + et * 64 + ec);
;       float kr[4] = {k4.x, k4.y, k4.z, k4.w}, aa[4] = {a4.x, a4.y, a4.z, a4.w}, rr[4] = {r4.x, r4.y, r4.z, r4.w};
;       float kk[4], ss = 0.f;
; #pragma unroll
;       for (int j = 0; j < 4; ++j) { kk[j] = kr[j] * kkw[j]; ss += kk[j] * kk[j]; }
	ds_read_b128 v[80:83], v197 offset:4096
	ds_read_b128 v[84:87], v197 offset:12288
	ds_read_b128 v[88:91], v197 offset:16384
	s_cmp_lg_u64 s[60:61], 0
	s_cbranch_scc0 .Lsp_pf
	s_waitcnt vmcnt(0)
.Lsp_pf:
	s_waitcnt vmcnt(10) lgkmcnt(2)
	v_pk_mul_f32 v[0:1], v[240:241], v[80:81]
	s_waitcnt lgkmcnt(1)
	v_pk_add_f32 v[68:69], v[84:85], -1.0 op_sel_hi:[1,0]
	v_pk_mul_f32 v[232:233], v[0:1], v[0:1]

; __device__ __forceinline__ void scan_item(const Params& p, int stream, int h, unsigned char* smem) {
;     ...
;       for (int j = 0; j < 4; ++j) { kk[j] = kr[j] * kkw[j]; ss += kk[j] * kk[j]; }
;       ss = row16_sum(ss);
;       const float inv = fminf(__builtin_amdgcn_rsqf(ss), 1e12f);
;       float kp[4], nk[4], ka[4], rk = 0.f;
; #pragma unroll
;       for (int j = 0; j < 4; ++j) {
;         kk[j] *= inv;
;         kp[j] = kr[j] * (1.f + (aa[j] - 1.f) * kaw[j]);
;         nk[j] = -kk[j]; ka[j] = kk[j] * aa[j];
;         rk += rr[j] * kp[j] * rkw[j];
	v_pk_fma_f32 v[68:69], v[244:245], v[68:69], 1.0 op_sel_hi:[1,1,0]
	s_nop 0
	v_pk_mul_f32 v[68:69], v[80:81], v[68:69]
	s_waitcnt lgkmcnt(0)
	v_mul_f32_e32 v3, v68, v88

; __device__ __forceinline__ void scan_item(const Params& p, int stream, int h, unsigned char* smem) {
;     ...
;       ss = row16_sum(ss);
;       const float inv = fminf(__builtin_amdgcn_rsqf(ss), 1e12f);
;       float kp[4], nk[4], ka[4], rk = 0.f;
; #pragma unroll
;       for (int j = 0; j < 4; ++j) {
;         kk[j] *= inv;
;         kp[j] = kr[j] * (1.f + (aa[j] - 1.f) * kaw[j]);
;         nk[j] = -kk[j]; ka[j] = kk[j] * aa[j];
;         rk += rr[j] * kp[j] * rkw[j];
;       }
;       rk = row16_sum(rk);
;       *(float4*)(sKp + et * 64 + ec) = make_float4(kp[0], kp[1], kp[2], kp[3]);
;       *(float4*)(sNKK + et * 64 + ec) = make_float4(nk[0], nk[1], nk[2], nk[3]);
;       *(float4*)(sKKA + et * 64 + ec) = make_float4(ka[0], ka[1], ka[2], ka[3]);
;       if ((tid & 15) == 0) sRK[et] = rk;
;     }
;     __syncthreads();
;     {
;       const int k = tid & 63, tq = tid >> 6;
;       float gam = 1.f;
;       {
;         float wv[12];
; #pragma unroll
;         for (int t = 0; t < 12; ++t) wv[t] = sW[t * 64 + k];
; #pragma unroll
;         for (int t = 0; t < 12; ++t) gam *= (t < 4 * tq) ? wv[t] : 1.f;
	v_fma_f32 v3, v248, v3, 0
	v_mul_f32_e32 v72, v69, v89
	v_fmac_f32_e32 v3, v249, v72
	v_pk_mul_f32 v[72:73], v[242:243], v[82:83]
	v_pk_add_f32 v[70:71], v[86:87], -1.0 op_sel_hi:[1,0]
	v_pk_mul_f32 v[76:77], v[72:73], v[72:73]
	v_pk_fma_f32 v[70:71], v[246:247], v[70:71], 1.0 op_sel_hi:[1,1,0]
	v_add_f32_e32 v74, v232, v233
	v_add_f32_e32 v74, v74, v76
	v_add_f32_e32 v74, v74, v77
	v_pk_mul_f32 v[70:71], v[82:83], v[70:71]
	ds_write_b128 v197, v[68:71] offset:4096
	v_add_f32_dpp v74, v74, v74 quad_perm:[1,0,3,2] row_mask:0xf bank_mask:0xf bound_ctrl:1
	v_mul_f32_e32 v76, v70, v90
	v_mul_f32_e32 v77, v71, v91
	v_add_f32_dpp v74, v74, v74 quad_perm:[2,3,0,1] row_mask:0xf bank_mask:0xf bound_ctrl:1
	v_fmac_f32_e32 v3, v250, v76
	v_fmac_f32_e32 v3, v251, v77
	v_add_f32_dpp v74, v74, v74 row_half_mirror row_mask:0xf bank_mask:0xf bound_ctrl:1
	s_nop 1
	v_add_f32_dpp v74, v74, v74 row_mirror row_mask:0xf bank_mask:0xf bound_ctrl:1
	v_rsq_f32_e32 v74, v74
	s_nop 0
	v_min_f32_e32 v70, 0x5368d4a5, v74
	v_pk_mul_f32 v[74:75], v[0:1], v[70:71] op_sel_hi:[1,0]
	v_add_f32_dpp v0, v3, v3 quad_perm:[1,0,3,2] row_mask:0xf bank_mask:0xf bound_ctrl:1
	v_pk_mul_f32 v[72:73], v[72:73], v[70:71] op_sel_hi:[1,0]
	v_xor_b32_e32 v69, 0x80000000, v75
	v_add_f32_dpp v0, v0, v0 quad_perm:[2,3,0,1] row_mask:0xf bank_mask:0xf bound_ctrl:1
	v_xor_b32_e32 v68, 0x80000000, v74
	v_xor_b32_e32 v71, 0x80000000, v73
	v_xor_b32_e32 v70, 0x80000000, v72
	v_add_f32_dpp v0, v0, v0 row_half_mirror row_mask:0xf bank_mask:0xf bound_ctrl:1
	v_mov_b32_e32 v1, v2
	ds_write_b128 v197, v[68:71] offset:8192
	v_pk_mul_f32 v[68:69], v[84:85], v[74:75]
	v_mov_b32_dpp v1, v0 row_mirror row_mask:0xf bank_mask:0xf
	v_pk_mul_f32 v[70:71], v[86:87], v[72:73]
	ds_write_b128 v197, v[68:71] offset:12288
	s_and_saveexec_b64 s[0:1], s[20:21]
	v_add_f32_e32 v0, v0, v1
	ds_write_b32 v99, v0 offset:32768
	s_or_b64 exec, exec, s[0:1]
	s_waitcnt lgkmcnt(0)
	s_barrier
	ds_read2st64_b32 v[72:73], v199 offset0:4 offset1:5
	ds_read2st64_b32 v[70:71], v199 offset0:6 offset1:7
	ds_read2st64_b32 v[68:69], v199 offset0:8 offset1:9
	ds_read2st64_b32 v[0:1], v199 offset0:10 offset1:11
	v_mov_b32_e32 v3, 1.0
	s_and_saveexec_b64 s[0:1], s[58:59]
	s_cbranch_execz .LBB0_1599
	ds_read2st64_b32 v[74:75], v199 offset1:1
	ds_read2st64_b32 v[76:77], v199 offset0:2 offset1:3
	s_waitcnt lgkmcnt(1)
	v_mul_f32_e32 v3, v75, v74
	s_waitcnt lgkmcnt(0)
	v_mul_f32_e32 v3, v76, v3
	v_mul_f32_e32 v3, v77, v3
